# P1 input projection: N-tile index permuted so every block group gets a balanced mix of epilogue types (measured per-type epilogue costs), removing barrier wait on the slowest group
# speedup vs baseline: 1.0098x; 1.0098x over previous
.LBB0_407:
	s_add_i32 s4, s4, s39
	s_mul_hi_u32 s5, s4, 0xaaaaaaab
	s_lshr_b32 s5, s5, 6
	s_lshl_b32 s8, s5, 3
	s_mulk_i32 s5, 0x60
	s_sub_i32 s4, s4, s5
	s_and_b32 s5, s4, 7
	s_or_b32 s66, s8, s5
	s_lshr_b32 s38, s4, 3
	s_mov_b32 s12, 0x75416320
	s_mov_b32 s13, 0x9ba8
	s_lshl_b32 s32, s38, 2
	s_lshr_b64 s[14:15], s[12:13], s32
	s_and_b32 s38, s14, 15
	s_and_b64 vcc, exec, s[6:7]
	s_mov_b64 s[4:5], -1
	s_cbranch_vccnz .LBB0_404
